# v18 + the 128 canonicalising v_max_f32 vN,vN,vN of the P12 squared-ReLU epilogue removed (max(0,x) follows each); 6 s_nop pads keep the store-data wait states
# speedup vs baseline: 1.0078x; 1.0042x over previous
.LBB0_1218:
	v_lshl_add_u32 v150, s26, 8, v152
	s_lshl_b32 s19, s27, 8
	v_max_f32_e32 v129, 0, v129
	v_max_f32_e32 v128, 0, v128
	s_or_b32 s19, s19, s44
	v_ashrrev_i32_e32 v151, 31, v150
	v_max_f32_e32 v125, 0, v125
	v_max_f32_e32 v124, 0, v124
	v_pk_mul_f32 v[128:129], v[128:129], v[128:129]
	v_max_f32_e32 v127, 0, v127
	v_max_f32_e32 v126, 0, v126
	v_max_f32_e32 v123, 0, v123
	v_max_f32_e32 v122, 0, v122
	v_pk_mul_f32 v[160:161], v[124:125], v[124:125]
	v_cvt_pk_bf16_f32 v125, v128, v129
	v_lshlrev_b64 v[128:129], 1, v[150:151]
	s_ashr_i32 s26, s19, 6
	v_pk_mul_f32 v[126:127], v[126:127], v[126:127]
	v_pk_mul_f32 v[122:123], v[122:123], v[122:123]
	v_and_b32_e32 v128, 0xffffff00, v128
	s_ashr_i32 s27, s26, 31
	v_cvt_pk_bf16_f32 v124, v126, v127
	v_cvt_pk_bf16_f32 v126, v122, v123
	v_lshl_add_u64 v[122:123], v[128:129], 0, s[26:27]
	v_lshlrev_b64 v[122:123], 14, v[122:123]
	v_lshlrev_b32_e32 v151, 7, v150
	v_lshl_add_u64 v[122:123], s[84:85], 0, v[122:123]
	v_and_b32_e32 v138, 0x2780, v151
	v_cvt_pk_bf16_f32 v127, v160, v161
	v_lshl_add_u64 v[160:161], v[122:123], 0, v[138:139]
	v_mov_b32_e32 v149, v139
	v_max_f32_e32 v119, 0, v119
	v_max_f32_e32 v118, 0, v118
	s_or_b32 s28, s26, 2
	v_lshl_add_u64 v[160:161], v[160:161], 0, v[148:149]
	v_max_f32_e32 v115, 0, v115
	v_max_f32_e32 v114, 0, v114
	v_max_f32_e32 v117, 0, v117
	v_max_f32_e32 v116, 0, v116
	v_pk_mul_f32 v[118:119], v[118:119], v[118:119]
	s_ashr_i32 s29, s28, 31
	global_store_dwordx4 v[160:161], v[124:127], off
	s_nop 1
	v_pk_mul_f32 v[124:125], v[116:117], v[116:117]
	v_pk_mul_f32 v[116:117], v[114:115], v[114:115]
	v_cvt_pk_bf16_f32 v114, v118, v119
	v_lshl_add_u64 v[118:119], v[128:129], 0, s[28:29]
	v_max_f32_e32 v121, 0, v121
	v_max_f32_e32 v120, 0, v120
	v_lshlrev_b64 v[118:119], 14, v[118:119]
	v_pk_mul_f32 v[120:121], v[120:121], v[120:121]
	v_lshl_add_u64 v[118:119], s[84:85], 0, v[118:119]
	v_cvt_pk_bf16_f32 v115, v120, v121
	v_lshl_add_u64 v[120:121], v[118:119], 0, v[138:139]
	v_max_f32_e32 v111, 0, v111
	v_max_f32_e32 v110, 0, v110
	v_cvt_pk_bf16_f32 v116, v116, v117
	v_cvt_pk_bf16_f32 v117, v124, v125
	v_lshl_add_u64 v[120:121], v[120:121], 0, v[148:149]
	v_max_f32_e32 v113, 0, v113
	v_max_f32_e32 v112, 0, v112
	v_max_f32_e32 v107, 0, v107
	v_max_f32_e32 v106, 0, v106
	v_max_f32_e32 v109, 0, v109
	v_max_f32_e32 v108, 0, v108
	v_pk_mul_f32 v[110:111], v[110:111], v[110:111]
	v_bitop3_b32 v138, v151, s55, v157 bitop3:0xc8
	global_store_dwordx4 v[120:121], v[114:117], off
	v_pk_mul_f32 v[112:113], v[112:113], v[112:113]
	v_max_f32_e32 v103, 0, v103
	v_pk_mul_f32 v[114:115], v[108:109], v[108:109]
	v_pk_mul_f32 v[108:109], v[106:107], v[106:107]
	v_cvt_pk_bf16_f32 v106, v110, v111
	v_lshl_add_u64 v[110:111], v[122:123], 0, v[138:139]
	v_max_f32_e32 v102, 0, v102
	v_cvt_pk_bf16_f32 v107, v112, v113
	v_cvt_pk_bf16_f32 v108, v108, v109
	v_cvt_pk_bf16_f32 v109, v114, v115
	v_lshl_add_u64 v[110:111], v[110:111], 0, v[148:149]
	v_max_f32_e32 v105, 0, v105
	v_max_f32_e32 v104, 0, v104
	v_max_f32_e32 v99, 0, v99
	v_max_f32_e32 v98, 0, v98
	v_max_f32_e32 v101, 0, v101
	v_max_f32_e32 v100, 0, v100
	v_pk_mul_f32 v[102:103], v[102:103], v[102:103]
	global_store_dwordx4 v[110:111], v[106:109], off
	v_pk_mul_f32 v[104:105], v[104:105], v[104:105]
	v_max_f32_e32 v95, 0, v95
	v_pk_mul_f32 v[106:107], v[100:101], v[100:101]
	v_pk_mul_f32 v[100:101], v[98:99], v[98:99]
	v_cvt_pk_bf16_f32 v98, v102, v103
	v_lshl_add_u64 v[102:103], v[118:119], 0, v[138:139]
	v_max_f32_e32 v94, 0, v94
	v_cvt_pk_bf16_f32 v99, v104, v105
	v_cvt_pk_bf16_f32 v100, v100, v101
	v_cvt_pk_bf16_f32 v101, v106, v107
	v_lshl_add_u64 v[102:103], v[102:103], 0, v[148:149]
	v_max_f32_e32 v97, 0, v97
	v_max_f32_e32 v96, 0, v96
	v_max_f32_e32 v91, 0, v91
	v_max_f32_e32 v90, 0, v90
	v_max_f32_e32 v93, 0, v93
	v_max_f32_e32 v92, 0, v92
	v_pk_mul_f32 v[94:95], v[94:95], v[94:95]
	v_bitop3_b32 v138, v151, s55, v158 bitop3:0xc8
	global_store_dwordx4 v[102:103], v[98:101], off
	v_pk_mul_f32 v[96:97], v[96:97], v[96:97]
	v_max_f32_e32 v87, 0, v87
	v_pk_mul_f32 v[98:99], v[92:93], v[92:93]
	v_pk_mul_f32 v[92:93], v[90:91], v[90:91]
	v_cvt_pk_bf16_f32 v90, v94, v95
	v_lshl_add_u64 v[94:95], v[122:123], 0, v[138:139]
	v_max_f32_e32 v86, 0, v86
	v_cvt_pk_bf16_f32 v91, v96, v97
	v_cvt_pk_bf16_f32 v92, v92, v93
	v_cvt_pk_bf16_f32 v93, v98, v99
	v_lshl_add_u64 v[94:95], v[94:95], 0, v[148:149]
	v_max_f32_e32 v89, 0, v89
	v_max_f32_e32 v88, 0, v88
	v_max_f32_e32 v83, 0, v83
	v_max_f32_e32 v82, 0, v82
	v_max_f32_e32 v85, 0, v85
	v_max_f32_e32 v84, 0, v84
	v_pk_mul_f32 v[86:87], v[86:87], v[86:87]
	global_store_dwordx4 v[94:95], v[90:93], off
	v_pk_mul_f32 v[88:89], v[88:89], v[88:89]
	v_max_f32_e32 v79, 0, v79
	v_pk_mul_f32 v[90:91], v[84:85], v[84:85]
	v_pk_mul_f32 v[84:85], v[82:83], v[82:83]
	v_cvt_pk_bf16_f32 v82, v86, v87
	v_lshl_add_u64 v[86:87], v[118:119], 0, v[138:139]
	v_max_f32_e32 v78, 0, v78
	v_cvt_pk_bf16_f32 v83, v88, v89
	v_cvt_pk_bf16_f32 v84, v84, v85
	v_cvt_pk_bf16_f32 v85, v90, v91
	v_lshl_add_u64 v[86:87], v[86:87], 0, v[148:149]
	v_max_f32_e32 v81, 0, v81
	v_max_f32_e32 v80, 0, v80
	v_max_f32_e32 v75, 0, v75
	v_max_f32_e32 v74, 0, v74
	v_max_f32_e32 v77, 0, v77
	v_max_f32_e32 v76, 0, v76
	v_pk_mul_f32 v[78:79], v[78:79], v[78:79]
	v_bitop3_b32 v138, v151, s55, v159 bitop3:0xc8
	global_store_dwordx4 v[86:87], v[82:85], off
	v_pk_mul_f32 v[80:81], v[80:81], v[80:81]
	v_max_f32_e32 v71, 0, v71
	v_pk_mul_f32 v[82:83], v[76:77], v[76:77]
	v_pk_mul_f32 v[76:77], v[74:75], v[74:75]
	v_cvt_pk_bf16_f32 v74, v78, v79
	v_lshl_add_u64 v[78:79], v[122:123], 0, v[138:139]
	v_max_f32_e32 v70, 0, v70
	v_cvt_pk_bf16_f32 v75, v80, v81
	v_cvt_pk_bf16_f32 v76, v76, v77
	v_cvt_pk_bf16_f32 v77, v82, v83
	v_lshl_add_u64 v[78:79], v[78:79], 0, v[148:149]
	v_max_f32_e32 v73, 0, v73
	v_max_f32_e32 v72, 0, v72
	v_max_f32_e32 v67, 0, v67
	v_max_f32_e32 v66, 0, v66
	v_max_f32_e32 v69, 0, v69
	v_max_f32_e32 v68, 0, v68
	v_pk_mul_f32 v[70:71], v[70:71], v[70:71]
	global_store_dwordx4 v[78:79], v[74:77], off
	s_nop 1
	v_pk_mul_f32 v[72:73], v[72:73], v[72:73]
	v_pk_mul_f32 v[74:75], v[68:69], v[68:69]
	v_pk_mul_f32 v[68:69], v[66:67], v[66:67]
	v_cvt_pk_bf16_f32 v66, v70, v71
	v_lshl_add_u64 v[70:71], v[118:119], 0, v[138:139]
	v_cvt_pk_bf16_f32 v67, v72, v73
	v_cvt_pk_bf16_f32 v68, v68, v69
	v_cvt_pk_bf16_f32 v69, v74, v75
	v_lshl_add_u64 v[70:71], v[70:71], 0, v[148:149]
	global_store_dwordx4 v[70:71], v[66:69], off
	v_max_f32_e32 v63, 0, v63
	v_max_f32_e32 v62, 0, v62
	v_add_u32_e32 v66, 0x80, v150
	v_ashrrev_i32_e32 v67, 31, v66
	v_max_f32_e32 v59, 0, v59
	v_max_f32_e32 v58, 0, v58
	v_max_f32_e32 v61, 0, v61
	v_max_f32_e32 v60, 0, v60
	v_pk_mul_f32 v[62:63], v[62:63], v[62:63]
	v_max_f32_e32 v65, 0, v65
	v_max_f32_e32 v64, 0, v64
	v_pk_mul_f32 v[68:69], v[60:61], v[60:61]
	v_pk_mul_f32 v[60:61], v[58:59], v[58:59]
	v_cvt_pk_bf16_f32 v58, v62, v63
	v_lshlrev_b64 v[62:63], 1, v[66:67]
	v_pk_mul_f32 v[64:65], v[64:65], v[64:65]
	v_and_b32_e32 v62, 0xffffff00, v62
	v_cvt_pk_bf16_f32 v59, v64, v65
	v_lshl_add_u64 v[64:65], v[62:63], 0, s[26:27]
	v_lshlrev_b64 v[64:65], 14, v[64:65]
	v_lshlrev_b32_e32 v66, 7, v66
	v_lshl_add_u64 v[64:65], s[84:85], 0, v[64:65]
	v_and_b32_e32 v138, 0x3f80, v66
	v_lshl_add_u64 v[64:65], v[64:65], 0, v[138:139]
	v_max_f32_e32 v55, 0, v55
	v_max_f32_e32 v54, 0, v54
	v_cvt_pk_bf16_f32 v60, v60, v61
	v_cvt_pk_bf16_f32 v61, v68, v69
	v_lshl_add_u64 v[64:65], v[64:65], 0, v[148:149]
	v_max_f32_e32 v51, 0, v51
	v_max_f32_e32 v50, 0, v50
	v_max_f32_e32 v53, 0, v53
	v_max_f32_e32 v52, 0, v52
	v_pk_mul_f32 v[54:55], v[54:55], v[54:55]
	global_store_dwordx4 v[64:65], v[58:61], off
	s_nop 1
	v_pk_mul_f32 v[58:59], v[52:53], v[52:53]
	v_pk_mul_f32 v[52:53], v[50:51], v[50:51]
	v_cvt_pk_bf16_f32 v50, v54, v55
	v_lshl_add_u64 v[54:55], v[62:63], 0, s[28:29]
	v_lshlrev_b64 v[54:55], 14, v[54:55]
	v_max_f32_e32 v57, 0, v57
	v_max_f32_e32 v56, 0, v56
	v_lshl_add_u64 v[54:55], s[84:85], 0, v[54:55]
	v_pk_mul_f32 v[56:57], v[56:57], v[56:57]
	v_lshl_add_u64 v[54:55], v[54:55], 0, v[138:139]
	v_cvt_pk_bf16_f32 v51, v56, v57
	v_cvt_pk_bf16_f32 v52, v52, v53
	v_cvt_pk_bf16_f32 v53, v58, v59
	v_lshl_add_u64 v[54:55], v[54:55], 0, v[148:149]
	global_store_dwordx4 v[54:55], v[50:53], off
	v_max_f32_e32 v47, 0, v47
	v_max_f32_e32 v46, 0, v46
	v_add_u32_e32 v50, 0x90, v150
	v_ashrrev_i32_e32 v51, 31, v50
	v_max_f32_e32 v43, 0, v43
	v_max_f32_e32 v42, 0, v42
	v_max_f32_e32 v45, 0, v45
	v_max_f32_e32 v44, 0, v44
	v_pk_mul_f32 v[46:47], v[46:47], v[46:47]
	v_max_f32_e32 v49, 0, v49
	v_max_f32_e32 v48, 0, v48
	v_pk_mul_f32 v[52:53], v[44:45], v[44:45]
	v_pk_mul_f32 v[44:45], v[42:43], v[42:43]
	v_cvt_pk_bf16_f32 v42, v46, v47
	v_lshlrev_b64 v[46:47], 1, v[50:51]
	v_pk_mul_f32 v[48:49], v[48:49], v[48:49]
	v_and_b32_e32 v46, 0xffffff00, v46
	v_cvt_pk_bf16_f32 v43, v48, v49
	v_lshl_add_u64 v[48:49], v[46:47], 0, s[26:27]
	v_lshlrev_b64 v[48:49], 14, v[48:49]
	v_lshlrev_b32_e32 v50, 7, v50
	v_lshl_add_u64 v[48:49], s[84:85], 0, v[48:49]
	v_and_b32_e32 v138, 0x3f80, v50
	v_lshl_add_u64 v[48:49], v[48:49], 0, v[138:139]
	v_max_f32_e32 v39, 0, v39
	v_max_f32_e32 v38, 0, v38
	v_cvt_pk_bf16_f32 v44, v44, v45
	v_cvt_pk_bf16_f32 v45, v52, v53
	v_lshl_add_u64 v[48:49], v[48:49], 0, v[148:149]
	v_max_f32_e32 v35, 0, v35
	v_max_f32_e32 v34, 0, v34
	v_max_f32_e32 v37, 0, v37
	v_max_f32_e32 v36, 0, v36
	v_pk_mul_f32 v[38:39], v[38:39], v[38:39]
	global_store_dwordx4 v[48:49], v[42:45], off
	s_nop 1
	v_pk_mul_f32 v[42:43], v[36:37], v[36:37]
	v_pk_mul_f32 v[36:37], v[34:35], v[34:35]
	v_cvt_pk_bf16_f32 v34, v38, v39
	v_lshl_add_u64 v[38:39], v[46:47], 0, s[28:29]
	v_lshlrev_b64 v[38:39], 14, v[38:39]
	v_max_f32_e32 v41, 0, v41
	v_max_f32_e32 v40, 0, v40
	v_lshl_add_u64 v[38:39], s[84:85], 0, v[38:39]
	v_pk_mul_f32 v[40:41], v[40:41], v[40:41]
	v_lshl_add_u64 v[38:39], v[38:39], 0, v[138:139]
	v_cvt_pk_bf16_f32 v35, v40, v41
	v_cvt_pk_bf16_f32 v36, v36, v37
	v_cvt_pk_bf16_f32 v37, v42, v43
	v_lshl_add_u64 v[38:39], v[38:39], 0, v[148:149]
	global_store_dwordx4 v[38:39], v[34:37], off
	v_max_f32_e32 v31, 0, v31
	v_max_f32_e32 v30, 0, v30
	v_add_u32_e32 v34, 0xa0, v150
	v_ashrrev_i32_e32 v35, 31, v34
	v_max_f32_e32 v27, 0, v27
	v_max_f32_e32 v26, 0, v26
	v_max_f32_e32 v29, 0, v29
	v_max_f32_e32 v28, 0, v28
	v_pk_mul_f32 v[30:31], v[30:31], v[30:31]
	v_max_f32_e32 v33, 0, v33
	v_max_f32_e32 v32, 0, v32
	v_pk_mul_f32 v[36:37], v[28:29], v[28:29]
	v_pk_mul_f32 v[28:29], v[26:27], v[26:27]
	v_cvt_pk_bf16_f32 v26, v30, v31
	v_lshlrev_b64 v[30:31], 1, v[34:35]
	v_pk_mul_f32 v[32:33], v[32:33], v[32:33]
	v_and_b32_e32 v30, 0xffffff00, v30
	v_cvt_pk_bf16_f32 v27, v32, v33
	v_lshl_add_u64 v[32:33], v[30:31], 0, s[26:27]
	v_lshlrev_b64 v[32:33], 14, v[32:33]
	v_lshlrev_b32_e32 v34, 7, v34
	v_lshl_add_u64 v[32:33], s[84:85], 0, v[32:33]
	v_and_b32_e32 v138, 0x3f80, v34
	v_lshl_add_u64 v[32:33], v[32:33], 0, v[138:139]
	v_max_f32_e32 v23, 0, v23
	v_max_f32_e32 v22, 0, v22
	v_cvt_pk_bf16_f32 v28, v28, v29
	v_cvt_pk_bf16_f32 v29, v36, v37
	v_lshl_add_u64 v[32:33], v[32:33], 0, v[148:149]
	v_max_f32_e32 v19, 0, v19
	v_max_f32_e32 v18, 0, v18
	v_max_f32_e32 v21, 0, v21
	v_max_f32_e32 v20, 0, v20
	v_pk_mul_f32 v[22:23], v[22:23], v[22:23]
	global_store_dwordx4 v[32:33], v[26:29], off
	s_nop 1
	v_pk_mul_f32 v[26:27], v[20:21], v[20:21]
	v_pk_mul_f32 v[20:21], v[18:19], v[18:19]
	v_cvt_pk_bf16_f32 v18, v22, v23
	v_lshl_add_u64 v[22:23], v[30:31], 0, s[28:29]
	v_lshlrev_b64 v[22:23], 14, v[22:23]
	v_max_f32_e32 v25, 0, v25
	v_max_f32_e32 v24, 0, v24
	v_lshl_add_u64 v[22:23], s[84:85], 0, v[22:23]
	v_pk_mul_f32 v[24:25], v[24:25], v[24:25]
	v_lshl_add_u64 v[22:23], v[22:23], 0, v[138:139]
	v_cvt_pk_bf16_f32 v19, v24, v25
	v_cvt_pk_bf16_f32 v20, v20, v21
	v_cvt_pk_bf16_f32 v21, v26, v27
	v_lshl_add_u64 v[22:23], v[22:23], 0, v[148:149]
	global_store_dwordx4 v[22:23], v[18:21], off
	v_max_f32_e32 v15, 0, v15
	v_max_f32_e32 v14, 0, v14
	v_add_u32_e32 v18, 0xb0, v150
	v_ashrrev_i32_e32 v19, 31, v18
	v_max_f32_e32 v11, 0, v11
	v_max_f32_e32 v10, 0, v10
	v_max_f32_e32 v13, 0, v13
	v_max_f32_e32 v12, 0, v12
	v_pk_mul_f32 v[14:15], v[14:15], v[14:15]
	v_max_f32_e32 v17, 0, v17
	v_max_f32_e32 v16, 0, v16
	v_pk_mul_f32 v[20:21], v[12:13], v[12:13]
	v_pk_mul_f32 v[12:13], v[10:11], v[10:11]
	v_cvt_pk_bf16_f32 v10, v14, v15
	v_lshlrev_b64 v[14:15], 1, v[18:19]
	v_pk_mul_f32 v[16:17], v[16:17], v[16:17]
	v_and_b32_e32 v14, 0xffffff00, v14
	v_cvt_pk_bf16_f32 v11, v16, v17
	v_lshl_add_u64 v[16:17], v[14:15], 0, s[26:27]
	v_lshlrev_b64 v[16:17], 14, v[16:17]
	v_lshlrev_b32_e32 v18, 7, v18
	v_lshl_add_u64 v[16:17], s[84:85], 0, v[16:17]
	v_and_b32_e32 v138, 0x3f80, v18
	v_lshl_add_u64 v[16:17], v[16:17], 0, v[138:139]
	v_max_f32_e32 v7, 0, v7
	v_max_f32_e32 v6, 0, v6
	v_cvt_pk_bf16_f32 v12, v12, v13
	v_cvt_pk_bf16_f32 v13, v20, v21
	v_lshl_add_u64 v[16:17], v[16:17], 0, v[148:149]
	v_max_f32_e32 v3, 0, v3
	v_max_f32_e32 v2, 0, v2
	v_max_f32_e32 v5, 0, v5
	v_max_f32_e32 v4, 0, v4
	v_pk_mul_f32 v[6:7], v[6:7], v[6:7]
	global_store_dwordx4 v[16:17], v[10:13], off
	s_nop 1
	v_pk_mul_f32 v[10:11], v[4:5], v[4:5]
	v_pk_mul_f32 v[4:5], v[2:3], v[2:3]
	v_cvt_pk_bf16_f32 v2, v6, v7
	v_lshl_add_u64 v[6:7], v[14:15], 0, s[28:29]
	v_lshlrev_b64 v[6:7], 14, v[6:7]
	v_max_f32_e32 v9, 0, v9
	v_max_f32_e32 v8, 0, v8
	v_lshl_add_u64 v[6:7], s[84:85], 0, v[6:7]
	v_pk_mul_f32 v[8:9], v[8:9], v[8:9]
	v_lshl_add_u64 v[6:7], v[6:7], 0, v[138:139]
	v_cvt_pk_bf16_f32 v3, v8, v9
	v_cvt_pk_bf16_f32 v4, v4, v5
	v_cvt_pk_bf16_f32 v5, v10, v11
	v_lshl_add_u64 v[6:7], v[6:7], 0, v[148:149]
	s_andn2_b64 vcc, exec, s[4:5]
	s_mov_b64 s[4:5], -1
	global_store_dwordx4 v[6:7], v[2:5], off
	s_cbranch_vccnz .LBB0_1207
	s_andn2_b64 vcc, exec, s[6:7]
	s_cbranch_vccnz .LBB0_1206
	s_barrier
	s_branch .LBB0_1206
